# v2: one static s_setprio 1 for waves 4-7 during the MLA attention phase (reset to 0 before the grid barrier)
# speedup vs baseline: 1.0074x; 1.0065x over previous
.LBB0_2402:
	s_or_b64 exec, exec, s[10:11]
	s_waitcnt lgkmcnt(0)
	s_barrier
	v_readfirstlane_b32 s98, v0
	s_lshr_b32 s98, s98, 6
	s_cmp_lt_u32 s98, 4
	s_cbranch_scc1 .Lprio_skip_p28
	s_setprio 1
.Lprio_skip_p28:
	s_load_dwordx4 s[36:39], s[84:85], 0x100
	s_and_b32 s0, s74, 7
	s_ashr_i32 s4, s2, 3
	s_cmp_eq_u32 s0, 0
	s_cselect_b64 s[10:11], -1, 0
	s_and_b64 s[0:1], s[10:11], exec
	s_movk_i32 s6, 0x100
	s_cselect_b32 s5, s4, s2
	s_cselect_b32 s7, s6, 0x800
	s_lshl_b32 s4, s2, 8
	s_mov_b32 s16, 0
	s_cmp_lt_i32 s5, s7
	v_mov_b32_e32 v2, v0
	s_waitcnt lgkmcnt(0)
	s_mov_b32 s0, s37
	s_cbranch_scc0 .LBB0_2438
	s_ashr_i32 s9, s74, 3
	s_and_b32 s8, s4, 0x700
	s_and_b64 s[0:1], s[10:11], exec
	s_cselect_b32 s8, s8, 0
	s_cselect_b32 s9, s9, s74
	s_add_u32 s35, s38, 0x12100000
	s_addc_u32 s48, s39, 0
	s_add_u32 s49, s38, 0x1e100000
	s_addc_u32 s50, s39, 0
	s_add_u32 s51, s38, 0x2a100000
	s_addc_u32 s52, s39, 0
	s_add_u32 s53, s38, 0x32100000
	s_addc_u32 s54, s39, 0
	s_movk_i32 s55, 0xc0
	v_mov_b32_e32 v3, 0
	s_mov_b32 s56, 0x2aaaaaab
	s_add_i32 s57, 0, 0x8000
	s_mov_b32 s17, s16
	s_mov_b32 s18, s16
	s_mov_b32 s19, s16
	s_mov_b32 s20, s16
	s_mov_b32 s21, s16
	s_mov_b32 s22, s16
	s_mov_b32 s23, s16
	s_mov_b32 s24, s16
	s_mov_b32 s25, s16
	s_mov_b32 s26, s16
	s_mov_b32 s27, s16
	s_mov_b32 s28, s16
	s_mov_b32 s29, s16
	s_mov_b32 s30, s16
	s_mov_b32 s31, s16
	v_mov_b32_e32 v170, 0x7f7f7f7f
	s_mov_b32 s58, 0x42ddb3d8
	s_mov_b32 s34, 0x3dd53b94
	s_movk_i32 s59, 0x4000
	s_mov_b64 s[36:37], 0x6000
	v_mov_b32_e32 v171, 0xf149f2ca
	s_branch .LBB0_2405

.LBB0_2438:
	s_waitcnt vmcnt(0)
	s_setprio 0
	s_barrier
	s_and_saveexec_b64 s[10:11], s[92:93]
	s_cbranch_execz .LBB0_2490
	s_add_i32 s0, 0, 0x24020
	v_mov_b32_e32 v2, s0
	s_waitcnt vmcnt(0) expcnt(0) lgkmcnt(0)
	ds_read_b32 v4, v2
	s_add_i32 s0, 0, 0x24024
	v_mov_b32_e32 v2, s0
	ds_read_b32 v2, v2
	s_waitcnt lgkmcnt(1)
	v_cmp_ne_u32_e32 vcc, 0, v4
	s_cbranch_vccnz .LBB0_2454
	s_add_u32 s12, s82, 0x4200
	s_addc_u32 s13, s83, 0
	s_add_u32 s14, s82, 0x4400
	s_addc_u32 s15, s83, 0
	s_add_u32 s16, s82, 0x4500
	s_addc_u32 s17, s83, 0
	s_add_u32 s18, s82, 0x4600
	s_addc_u32 s19, s83, 0
	s_add_u32 s20, s82, 0x4700
	s_addc_u32 s21, s83, 0
	s_add_u32 s22, s82, 0x4800
	s_addc_u32 s23, s83, 0
	s_add_u32 s24, s82, 0x4900
	s_addc_u32 s25, s83, 0
	s_add_u32 s26, s82, 0x4a00
	s_addc_u32 s27, s83, 0
	s_add_u32 s28, s82, 0x4b00
	s_addc_u32 s29, s83, 0
	s_add_u32 s30, s82, 0x4c00
	s_addc_u32 s31, s83, 0
	s_add_u32 s34, s82, 0x4d00
	s_addc_u32 s35, s83, 0
	s_add_u32 s36, s82, 0x4e00
	s_addc_u32 s37, s83, 0
	s_add_u32 s38, s82, 0x4f00
	v_readlane_b32 s6, v254, 0
	s_addc_u32 s39, s83, 0
	v_readlane_b32 s7, v254, 1
	s_add_u32 s40, s82, 0x5000
	s_load_dwordx2 s[0:1], s[6:7], 0x4
	s_addc_u32 s41, s83, 0
	s_add_u32 s42, s82, 0x5100
	s_addc_u32 s43, s83, 0
	s_add_u32 s44, s82, 0x5200
	s_addc_u32 s45, s83, 0
	s_waitcnt lgkmcnt(0)
	s_mul_i32 s0, s0, s74
	s_add_u32 s46, s82, 0x5300
	s_mul_i32 s0, s0, s1
	s_addc_u32 s47, s83, 0
	s_mov_b32 s1, 1
	v_mov_b32_e32 v18, 0
	s_branch .LBB0_2442
